# v67 + F epilogue preamble loads prefetched from the second-to-last K-loop trip (no vmcnt(0) behind the LDS-DMA stream)
# baseline (speedup 1.0000x reference)
.LBB0_919:
	v_lshl_add_u64 v[154:155], s[6:7], 0, v[164:165]
	s_add_i32 m0, s43, 0xc000
	ds_read_b128 v[146:149], v253
	ds_read_b128 v[150:153], v253 offset:1024
	ds_read_b128 v[168:171], v253 offset:2048
	ds_read_b128 v[172:175], v253 offset:3072
	ds_read_b128 v[176:179], v253 offset:4096
	ds_read_b128 v[180:183], v253 offset:5120
	ds_read_b128 v[184:187], v253 offset:6144
	ds_read_b128 v[190:193], v253 offset:7168
	global_load_lds_dwordx4 v[154:155], off
	s_add_i32 m0, s43, 0xe000
	v_lshl_add_u64 v[154:155], s[6:7], 0, v[166:167]
	global_load_lds_dwordx4 v[154:155], off
	s_waitcnt lgkmcnt(8)
	s_barrier
	s_waitcnt lgkmcnt(0)
	v_mfma_f32_16x16x32_bf16 v[126:129], v[130:133], v[146:149], v[126:129]
	v_mfma_f32_16x16x32_bf16 v[70:73], v[138:141], v[146:149], v[70:73]
	v_mfma_f32_16x16x32_bf16 v[122:125], v[130:133], v[168:171], v[122:125]
	v_mfma_f32_16x16x32_bf16 v[74:77], v[138:141], v[168:171], v[74:77]
	v_mfma_f32_16x16x32_bf16 v[114:117], v[130:133], v[176:179], v[114:117]
	v_mfma_f32_16x16x32_bf16 v[66:69], v[138:141], v[176:179], v[66:69]
	v_mfma_f32_16x16x32_bf16 v[110:113], v[130:133], v[184:187], v[110:113]
	v_mfma_f32_16x16x32_bf16 v[78:81], v[138:141], v[184:187], v[78:81]
	v_mfma_f32_16x16x32_bf16 v[126:129], v[134:137], v[150:153], v[126:129]
	v_mfma_f32_16x16x32_bf16 v[70:73], v[142:145], v[150:153], v[70:73]
	v_mfma_f32_16x16x32_bf16 v[122:125], v[134:137], v[172:175], v[122:125]
	v_mfma_f32_16x16x32_bf16 v[74:77], v[142:145], v[172:175], v[74:77]
	v_mfma_f32_16x16x32_bf16 v[114:117], v[134:137], v[180:183], v[114:117]
	v_mfma_f32_16x16x32_bf16 v[66:69], v[142:145], v[180:183], v[66:69]
	v_mfma_f32_16x16x32_bf16 v[110:113], v[134:137], v[190:193], v[110:113]
	v_mfma_f32_16x16x32_bf16 v[78:81], v[142:145], v[190:193], v[78:81]
	s_barrier
	s_add_i32 vcc_hi, 0, 0x14000
	s_add_i32 s6, vcc_lo, s39
	v_add_u32_e32 v0, vcc_hi, v254
	v_lshl_add_u64 v[154:155], s[90:91], 0, v[160:161]
	s_mov_b32 m0, s6
	ds_read_b128 v[194:197], v0
	ds_read_b128 v[198:201], v0 offset:1024
	ds_read_b128 v[202:205], v0 offset:2048
	ds_read_b128 v[206:209], v0 offset:3072
	global_load_lds_dwordx4 v[154:155], off
	s_add_i32 m0, s6, 0x2000
	v_lshl_add_u64 v[210:211], s[90:91], 0, v[156:157]
	global_load_lds_dwordx4 v[210:211], off
	s_cmp_eq_u32 s45, 10
	s_cbranch_scc0 .Lfp_skip
	v_bfe_u32 v238, v252, 4, 2
	v_and_b32_e32 v239, 15, v252
	v_lshlrev_b32_e32 v240, 4, v238
	v_or3_b32 v240, v240, s97, v239
	v_lshrrev_b32_e32 v241, 1, v240
	v_and_b32_e32 v242, 1, v252
	v_mul_u32_u24_e32 v243, 0xb00, v242
	s_lshl_b32 s32, s5, 9
	s_add_u32 s100, s73, s32
	s_addc_u32 s101, s74, 0
	v_add_u32_e32 v244, v241, v243
	v_lshlrev_b32_e32 v244, 2, v244
	v_mov_b32_e32 v245, 0
	v_lshl_add_u64 v[246:247], s[100:101], 0, v[244:245]
	v_mov_b32_e32 v248, 0x5800
	v_mov_b32_e32 v249, 0
	global_load_dword v224, v[246:247], off
	v_lshl_add_u64 v[250:251], v[246:247], 0, v[248:249]
	s_lshl_b32 s32, s5, 7
	global_load_dword v225, v[250:251], off
	v_lshl_add_u64 v[246:247], v[250:251], 0, v[248:249]
	v_add3_u32 v244, s32, v243, v241
	global_load_dword v226, v[246:247], off
	v_lshl_add_u64 v[250:251], v[244:245], 2, s[12:13]
	v_and_b32_e32 v244, 63, v252
	global_load_dword v227, v[250:251], off
	v_or_b32_e32 v244, s97, v244
	v_lshrrev_b32_e32 v244, 1, v244
	v_and_or_b32 v244, v244, 63, s55
	s_lshl_b32 s32, s4, 8
	v_add_u32_e32 v244, s32, v244
	v_ashrrev_i32_e32 v245, 31, v244
	v_lshlrev_b64 v[244:245], 6, v[244:245]
	v_lshl_add_u64 v[244:245], s[10:11], 0, v[244:245]
	v_lshlrev_b32_e32 v248, 5, v242
	v_lshl_add_u64 v[244:245], v[244:245], 0, v[248:249]
	global_load_dwordx4 v[228:231], v[244:245], off offset:16
	global_load_dwordx4 v[234:237], v[244:245], off
.Lfp_skip:
	s_barrier
	s_waitcnt lgkmcnt(0)
	v_mfma_f32_16x16x32_bf16 v[118:121], v[194:197], v[146:149], v[118:121]
	v_mfma_f32_16x16x32_bf16 v[94:97], v[202:205], v[146:149], v[94:97]
	v_mfma_f32_16x16x32_bf16 v[106:109], v[194:197], v[168:171], v[106:109]
	v_mfma_f32_16x16x32_bf16 v[90:93], v[202:205], v[168:171], v[90:93]
	v_mfma_f32_16x16x32_bf16 v[102:105], v[194:197], v[176:179], v[102:105]
	v_mfma_f32_16x16x32_bf16 v[82:85], v[202:205], v[176:179], v[82:85]
	v_mfma_f32_16x16x32_bf16 v[98:101], v[194:197], v[184:187], v[98:101]
	v_mfma_f32_16x16x32_bf16 v[86:89], v[202:205], v[184:187], v[86:89]
	v_mfma_f32_16x16x32_bf16 v[118:121], v[198:201], v[150:153], v[118:121]
	v_mfma_f32_16x16x32_bf16 v[94:97], v[206:209], v[150:153], v[94:97]
	v_mfma_f32_16x16x32_bf16 v[106:109], v[198:201], v[172:175], v[106:109]
	v_mfma_f32_16x16x32_bf16 v[90:93], v[206:209], v[172:175], v[90:93]
	v_mfma_f32_16x16x32_bf16 v[102:105], v[198:201], v[180:183], v[102:105]
	v_mfma_f32_16x16x32_bf16 v[82:85], v[206:209], v[180:183], v[82:85]
	v_mfma_f32_16x16x32_bf16 v[98:101], v[198:201], v[190:193], v[98:101]
	v_mfma_f32_16x16x32_bf16 v[86:89], v[206:209], v[190:193], v[86:89]
	s_mov_b32 m0, s43
	v_lshl_add_u64 v[212:213], s[92:93], 0, v[162:163]
	s_barrier
	ds_read_b128 v[146:149], v253 offset:16384
	ds_read_b128 v[150:153], v253 offset:17408
	ds_read_b128 v[168:171], v253 offset:18432
	ds_read_b128 v[172:175], v253 offset:19456
	ds_read_b128 v[176:179], v253 offset:20480
	ds_read_b128 v[180:183], v253 offset:21504
	ds_read_b128 v[184:187], v253 offset:22528
	ds_read_b128 v[190:193], v253 offset:23552
	global_load_lds_dwordx4 v[212:213], off
	s_mov_b32 m0, s60
	v_lshl_add_u64 v[214:215], s[92:93], 0, v[158:159]
	global_load_lds_dwordx4 v[214:215], off
	s_waitcnt vmcnt(10)
	s_barrier
	s_waitcnt lgkmcnt(0)
	v_mfma_f32_16x16x32_bf16 v[62:65], v[130:133], v[146:149], v[62:65]
	v_mfma_f32_16x16x32_bf16 v[10:13], v[138:141], v[146:149], v[10:13]
	v_mfma_f32_16x16x32_bf16 v[58:61], v[130:133], v[168:171], v[58:61]
	v_mfma_f32_16x16x32_bf16 v[14:17], v[138:141], v[168:171], v[14:17]
	v_mfma_f32_16x16x32_bf16 v[54:57], v[130:133], v[176:179], v[54:57]
	v_mfma_f32_16x16x32_bf16 v[6:9], v[138:141], v[176:179], v[6:9]
	v_mfma_f32_16x16x32_bf16 v[42:45], v[130:133], v[184:187], v[42:45]
	v_mfma_f32_16x16x32_bf16 v[2:5], v[138:141], v[184:187], v[2:5]
	v_mfma_f32_16x16x32_bf16 v[62:65], v[134:137], v[150:153], v[62:65]
	v_mfma_f32_16x16x32_bf16 v[10:13], v[142:145], v[150:153], v[10:13]
	v_mfma_f32_16x16x32_bf16 v[58:61], v[134:137], v[172:175], v[58:61]
	v_mfma_f32_16x16x32_bf16 v[14:17], v[142:145], v[172:175], v[14:17]
	v_mfma_f32_16x16x32_bf16 v[54:57], v[134:137], v[180:183], v[54:57]
	v_mfma_f32_16x16x32_bf16 v[6:9], v[142:145], v[180:183], v[6:9]
	v_mfma_f32_16x16x32_bf16 v[42:45], v[134:137], v[190:193], v[42:45]
	v_mfma_f32_16x16x32_bf16 v[2:5], v[142:145], v[190:193], v[2:5]
	s_barrier
	s_add_u32 s6, s90, 0x40000
	s_addc_u32 s7, s91, 0
	s_add_i32 vcc_lo, vcc_hi, s39
	s_mov_b32 m0, vcc_lo
	v_lshl_add_u64 v[130:131], s[6:7], 0, v[160:161]
	global_load_lds_dwordx4 v[130:131], off
	s_add_i32 m0, vcc_lo, 0x2000
	v_lshl_add_u64 v[130:131], s[6:7], 0, v[156:157]
	global_load_lds_dwordx4 v[130:131], off
	s_add_i32 vcc_lo, 0, 0x18000
	v_add_u32_e32 v0, vcc_lo, v254
	ds_read_b128 v[130:133], v0
	ds_read_b128 v[134:137], v0 offset:1024
	ds_read_b128 v[138:141], v0 offset:2048
	ds_read_b128 v[142:145], v0 offset:3072
	s_waitcnt vmcnt(6)
	s_barrier
	v_mfma_f32_16x16x32_bf16 v[50:53], v[194:197], v[146:149], v[50:53]
	v_mfma_f32_16x16x32_bf16 v[26:29], v[202:205], v[146:149], v[26:29]
	v_mfma_f32_16x16x32_bf16 v[46:49], v[194:197], v[168:171], v[46:49]
	v_mfma_f32_16x16x32_bf16 v[30:33], v[202:205], v[168:171], v[30:33]
	v_mfma_f32_16x16x32_bf16 v[38:41], v[194:197], v[176:179], v[38:41]
	v_mfma_f32_16x16x32_bf16 v[22:25], v[202:205], v[176:179], v[22:25]
	v_mfma_f32_16x16x32_bf16 v[34:37], v[194:197], v[184:187], v[34:37]
	v_mfma_f32_16x16x32_bf16 v[18:21], v[202:205], v[184:187], v[18:21]
	v_mfma_f32_16x16x32_bf16 v[50:53], v[198:201], v[150:153], v[50:53]
	v_mfma_f32_16x16x32_bf16 v[26:29], v[206:209], v[150:153], v[26:29]
	v_mfma_f32_16x16x32_bf16 v[46:49], v[198:201], v[172:175], v[46:49]
	v_mfma_f32_16x16x32_bf16 v[30:33], v[206:209], v[172:175], v[30:33]
	v_mfma_f32_16x16x32_bf16 v[38:41], v[198:201], v[180:183], v[38:41]
	v_mfma_f32_16x16x32_bf16 v[22:25], v[206:209], v[180:183], v[22:25]
	v_mfma_f32_16x16x32_bf16 v[34:37], v[198:201], v[190:193], v[34:37]
	v_mfma_f32_16x16x32_bf16 v[18:21], v[206:209], v[190:193], v[18:21]
	s_barrier
	s_add_u32 s6, s92, 0x40000
	s_addc_u32 s7, s93, 0
	s_mov_b32 m0, s61
	v_lshl_add_u64 v[194:195], s[6:7], 0, v[162:163]
	ds_read_b128 v[146:149], v253 offset:32768
	ds_read_b128 v[150:153], v253 offset:33792
	ds_read_b128 v[168:171], v253 offset:34816
	ds_read_b128 v[172:175], v253 offset:35840
	ds_read_b128 v[176:179], v253 offset:36864
	ds_read_b128 v[180:183], v253 offset:37888
	ds_read_b128 v[184:187], v253 offset:38912
	ds_read_b128 v[190:193], v253 offset:39936
	global_load_lds_dwordx4 v[194:195], off
	s_mov_b32 m0, s72
	v_lshl_add_u64 v[194:195], s[6:7], 0, v[158:159]
	global_load_lds_dwordx4 v[194:195], off
	s_waitcnt lgkmcnt(8)
	s_barrier
	s_waitcnt lgkmcnt(0)
	v_mfma_f32_16x16x32_bf16 v[126:129], v[130:133], v[146:149], v[126:129]
	v_mfma_f32_16x16x32_bf16 v[70:73], v[138:141], v[146:149], v[70:73]
	v_mfma_f32_16x16x32_bf16 v[122:125], v[130:133], v[168:171], v[122:125]
	v_mfma_f32_16x16x32_bf16 v[74:77], v[138:141], v[168:171], v[74:77]
	v_mfma_f32_16x16x32_bf16 v[114:117], v[130:133], v[176:179], v[114:117]
	v_mfma_f32_16x16x32_bf16 v[66:69], v[138:141], v[176:179], v[66:69]
	v_mfma_f32_16x16x32_bf16 v[110:113], v[130:133], v[184:187], v[110:113]
	v_mfma_f32_16x16x32_bf16 v[78:81], v[138:141], v[184:187], v[78:81]
	v_mfma_f32_16x16x32_bf16 v[126:129], v[134:137], v[150:153], v[126:129]
	v_mfma_f32_16x16x32_bf16 v[70:73], v[142:145], v[150:153], v[70:73]
	v_mfma_f32_16x16x32_bf16 v[122:125], v[134:137], v[172:175], v[122:125]
	v_mfma_f32_16x16x32_bf16 v[74:77], v[142:145], v[172:175], v[74:77]
	v_mfma_f32_16x16x32_bf16 v[114:117], v[134:137], v[180:183], v[114:117]
	v_mfma_f32_16x16x32_bf16 v[66:69], v[142:145], v[180:183], v[66:69]
	v_mfma_f32_16x16x32_bf16 v[110:113], v[134:137], v[190:193], v[110:113]
	v_mfma_f32_16x16x32_bf16 v[78:81], v[142:145], v[190:193], v[78:81]
	s_barrier
	s_add_i32 s92, 0, 0x1c000
	s_add_i32 s6, vcc_lo, s39
	v_add_u32_e32 v0, s92, v254
	v_lshl_add_u64 v[154:155], v[154:155], 0, s[40:41]
	s_mov_b32 m0, s6
	ds_read_b128 v[194:197], v0
	ds_read_b128 v[198:201], v0 offset:1024
	ds_read_b128 v[202:205], v0 offset:2048
	ds_read_b128 v[206:209], v0 offset:3072
	global_load_lds_dwordx4 v[154:155], off
	s_add_i32 m0, s6, 0x2000
	v_lshl_add_u64 v[154:155], v[210:211], 0, s[40:41]
	global_load_lds_dwordx4 v[154:155], off
	s_barrier
	s_waitcnt lgkmcnt(0)
	v_mfma_f32_16x16x32_bf16 v[118:121], v[194:197], v[146:149], v[118:121]
	v_mfma_f32_16x16x32_bf16 v[94:97], v[202:205], v[146:149], v[94:97]
	v_mfma_f32_16x16x32_bf16 v[106:109], v[194:197], v[168:171], v[106:109]
	v_mfma_f32_16x16x32_bf16 v[90:93], v[202:205], v[168:171], v[90:93]
	v_mfma_f32_16x16x32_bf16 v[102:105], v[194:197], v[176:179], v[102:105]
	v_mfma_f32_16x16x32_bf16 v[82:85], v[202:205], v[176:179], v[82:85]
	v_mfma_f32_16x16x32_bf16 v[98:101], v[194:197], v[184:187], v[98:101]
	v_mfma_f32_16x16x32_bf16 v[86:89], v[202:205], v[184:187], v[86:89]
	v_mfma_f32_16x16x32_bf16 v[118:121], v[198:201], v[150:153], v[118:121]
	v_mfma_f32_16x16x32_bf16 v[94:97], v[206:209], v[150:153], v[94:97]
	v_mfma_f32_16x16x32_bf16 v[106:109], v[198:201], v[172:175], v[106:109]
	v_mfma_f32_16x16x32_bf16 v[90:93], v[206:209], v[172:175], v[90:93]
	v_mfma_f32_16x16x32_bf16 v[102:105], v[198:201], v[180:183], v[102:105]
	v_mfma_f32_16x16x32_bf16 v[82:85], v[206:209], v[180:183], v[82:85]
	v_mfma_f32_16x16x32_bf16 v[98:101], v[198:201], v[190:193], v[98:101]
	v_mfma_f32_16x16x32_bf16 v[86:89], v[206:209], v[190:193], v[86:89]
	s_mov_b32 m0, s95
	v_lshl_add_u64 v[154:155], v[212:213], 0, s[40:41]
	s_barrier
	ds_read_b128 v[146:149], v253 offset:49152
	ds_read_b128 v[150:153], v253 offset:50176
	ds_read_b128 v[168:171], v253 offset:51200
	ds_read_b128 v[172:175], v253 offset:52224
	ds_read_b128 v[176:179], v253 offset:53248
	ds_read_b128 v[180:183], v253 offset:54272
	ds_read_b128 v[184:187], v253 offset:55296
	ds_read_b128 v[190:193], v253 offset:56320
	global_load_lds_dwordx4 v[154:155], off
	s_mov_b32 m0, s96
	v_lshl_add_u64 v[154:155], v[214:215], 0, s[40:41]
	global_load_lds_dwordx4 v[154:155], off
	s_waitcnt vmcnt(10)
	s_barrier
	s_waitcnt lgkmcnt(0)
	v_mfma_f32_16x16x32_bf16 v[62:65], v[130:133], v[146:149], v[62:65]
	v_mfma_f32_16x16x32_bf16 v[10:13], v[138:141], v[146:149], v[10:13]
	v_mfma_f32_16x16x32_bf16 v[58:61], v[130:133], v[168:171], v[58:61]
	v_mfma_f32_16x16x32_bf16 v[14:17], v[138:141], v[168:171], v[14:17]
	v_mfma_f32_16x16x32_bf16 v[54:57], v[130:133], v[176:179], v[54:57]
	v_mfma_f32_16x16x32_bf16 v[6:9], v[138:141], v[176:179], v[6:9]
	v_mfma_f32_16x16x32_bf16 v[42:45], v[130:133], v[184:187], v[42:45]
	v_mfma_f32_16x16x32_bf16 v[2:5], v[138:141], v[184:187], v[2:5]
	v_mfma_f32_16x16x32_bf16 v[62:65], v[134:137], v[150:153], v[62:65]
	v_mfma_f32_16x16x32_bf16 v[10:13], v[142:145], v[150:153], v[10:13]
	v_mfma_f32_16x16x32_bf16 v[58:61], v[134:137], v[172:175], v[58:61]
	v_mfma_f32_16x16x32_bf16 v[14:17], v[142:145], v[172:175], v[14:17]
	v_mfma_f32_16x16x32_bf16 v[54:57], v[134:137], v[180:183], v[54:57]
	v_mfma_f32_16x16x32_bf16 v[6:9], v[142:145], v[180:183], v[6:9]
	v_mfma_f32_16x16x32_bf16 v[42:45], v[134:137], v[190:193], v[42:45]
	v_mfma_f32_16x16x32_bf16 v[2:5], v[142:145], v[190:193], v[2:5]
	s_barrier
	s_add_u32 s6, s90, 0x40080
	s_addc_u32 s7, s91, 0
	s_add_i32 s90, s92, s39
	s_mov_b32 m0, s90
	v_lshl_add_u64 v[130:131], s[6:7], 0, v[160:161]
	global_load_lds_dwordx4 v[130:131], off
	s_add_i32 m0, s90, 0x2000
	v_lshl_add_u64 v[130:131], s[6:7], 0, v[156:157]
	global_load_lds_dwordx4 v[130:131], off
	s_add_i32 vcc_lo, 0, 0x10000
	v_add_u32_e32 v0, vcc_lo, v254
	ds_read_b128 v[130:133], v0
	ds_read_b128 v[134:137], v0 offset:1024
	ds_read_b128 v[138:141], v0 offset:2048
	ds_read_b128 v[142:145], v0 offset:3072
	s_waitcnt vmcnt(6)
	s_barrier
	v_mfma_f32_16x16x32_bf16 v[50:53], v[194:197], v[146:149], v[50:53]
	v_mfma_f32_16x16x32_bf16 v[26:29], v[202:205], v[146:149], v[26:29]
	v_mfma_f32_16x16x32_bf16 v[46:49], v[194:197], v[168:171], v[46:49]
	v_mfma_f32_16x16x32_bf16 v[30:33], v[202:205], v[168:171], v[30:33]
	v_mfma_f32_16x16x32_bf16 v[38:41], v[194:197], v[176:179], v[38:41]
	v_mfma_f32_16x16x32_bf16 v[22:25], v[202:205], v[176:179], v[22:25]
	v_mfma_f32_16x16x32_bf16 v[34:37], v[194:197], v[184:187], v[34:37]
	v_mfma_f32_16x16x32_bf16 v[18:21], v[202:205], v[184:187], v[18:21]
	v_mfma_f32_16x16x32_bf16 v[50:53], v[198:201], v[150:153], v[50:53]
	v_mfma_f32_16x16x32_bf16 v[26:29], v[206:209], v[150:153], v[26:29]
	v_mfma_f32_16x16x32_bf16 v[46:49], v[198:201], v[172:175], v[46:49]
	v_mfma_f32_16x16x32_bf16 v[30:33], v[206:209], v[172:175], v[30:33]
	v_mfma_f32_16x16x32_bf16 v[38:41], v[198:201], v[180:183], v[38:41]
	v_mfma_f32_16x16x32_bf16 v[22:25], v[206:209], v[180:183], v[22:25]
	v_mfma_f32_16x16x32_bf16 v[34:37], v[198:201], v[190:193], v[34:37]
	v_mfma_f32_16x16x32_bf16 v[18:21], v[206:209], v[190:193], v[18:21]
	s_add_i32 s45, s45, 2
	s_add_u32 s28, s28, 0x100
	s_addc_u32 s29, s29, 0
	s_mov_b64 s[6:7], s[88:89]
	s_add_u32 s88, s6, 0x100
	s_addc_u32 s89, s7, 0
	s_cmp_eq_u32 s45, 12
	s_cselect_b32 s93, s17, s89
	s_cselect_b32 s92, s22, s88
	s_cselect_b32 s91, s15, s29
	s_cselect_b32 s90, s23, s28
	s_cmp_gt_u32 s45, 13
	s_barrier
	s_cbranch_scc0 .LBB0_919
	s_waitcnt lgkmcnt(0)
	v_mov_b32_e32 v131, v252
	s_lshl_b32 s88, s5, 7
	v_bfe_u32 v130, v131, 4, 2
	v_and_b32_e32 v134, 15, v131
	v_lshlrev_b32_e32 v0, 4, v130
	s_ashr_i32 s89, s88, 31
	s_lshl_b32 s15, s4, 8
	v_or3_b32 v135, v0, s97, v134
	s_lshl_b64 s[4:5], s[88:89], 2
	v_lshrrev_b32_e32 v140, 1, v135
	s_add_u32 s4, s73, s4
	s_addc_u32 s5, s74, s5
	v_lshlrev_b32_e32 v0, 2, v140
	v_and_b32_e32 v144, 1, v131
	v_lshl_add_u64 v[132:133], s[4:5], 0, v[0:1]
	v_cmp_eq_u32_e32 vcc, 1, v144
	v_mov_b32_e32 v0, 0xb00
	s_movk_i32 s4, 0x5000
	v_cndmask_b32_e32 v141, 0, v0, vcc
	v_lshlrev_b32_e32 v0, 2, v141
	v_lshl_add_u64 v[132:133], v[132:133], 0, v[0:1]
	v_add_co_u32_e32 v138, vcc, s4, v132
	s_mov_b32 s4, 0xb000
	s_nop 0
	v_addc_co_u32_e32 v139, vcc, 0, v133, vcc
	v_mov_b32_e32 v136, v224
	v_mov_b32_e32 v137, v225
	v_add_co_u32_e32 v132, vcc, s4, v132
	v_add_u32_e32 v0, s88, v141
	s_nop 0
	v_addc_co_u32_e32 v133, vcc, 0, v133, vcc
	v_mov_b32_e32 v138, v226
	v_or_b32_e32 v132, v140, v0
	v_ashrrev_i32_e32 v133, 31, v132
	v_lshl_add_u64 v[132:133], v[132:133], 2, s[12:13]
	v_mov_b32_e32 v139, v227
	v_lshl_add_u32 v152, v135, 4, s78
	v_and_b32_e32 v135, 63, v131
	v_cmp_eq_u32_e32 vcc, 0, v144
	v_or_b32_e32 v0, s97, v135
	v_lshrrev_b32_e32 v0, 1, v0
	v_and_or_b32 v131, v0, 63, s55
	v_add_u32_e32 v132, s15, v131
	v_ashrrev_i32_e32 v133, 31, v132
	v_lshlrev_b64 v[132:133], 6, v[132:133]
	v_lshl_add_u64 v[132:133], s[10:11], 0, v[132:133]
	v_lshlrev_b32_e32 v0, 5, v144
	v_lshl_add_u64 v[132:133], v[132:133], 0, v[0:1]
	v_mov_b32_e32 v148, v228
	v_mov_b32_e32 v149, v229
	v_mov_b32_e32 v150, v230
	v_mov_b32_e32 v151, v231
	v_mov_b32_e32 v140, v234
	v_mov_b32_e32 v141, v235
	v_mov_b32_e32 v142, v236
	v_mov_b32_e32 v143, v237
	ds_write_b128 v152, v[136:139]
	v_add_f32_e32 v133, v150, v151
	v_add_f32_e32 v0, v140, v141
	v_add_f32_e32 v132, v142, v143
	v_add_f32_e32 v0, v0, v132
	v_add_f32_e32 v132, v148, v149
	v_add_f32_e32 v132, v132, v133
	v_add_f32_e32 v0, v0, v132
	v_lshlrev_b32_e32 v132, 2, v135
	v_xor_b32_e32 v132, 4, v132
	ds_bpermute_b32 v132, v132, v0
	s_and_saveexec_b64 s[4:5], vcc
	s_cbranch_execz .LBB0_922
	s_waitcnt lgkmcnt(0)
	v_add_f32_e32 v0, v0, v132
	v_mov_b32_e32 v132, 0x358637bd
	v_fmamk_f32 v0, v0, 0x3a800000, v132
	s_mov_b32 s6, 0x800000
	v_mul_f32_e32 v132, 0x4b800000, v0
	v_cmp_gt_f32_e32 vcc, s6, v0
	v_lshl_add_u32 v131, v131, 2, 0
	v_add_u32_e32 v131, 0x20000, v131
	v_cndmask_b32_e32 v0, v0, v132, vcc
	v_rsq_f32_e32 v0, v0
	s_nop 0
	v_mul_f32_e32 v132, 0x45800000, v0
	v_cndmask_b32_e32 v0, v0, v132, vcc
	ds_write_b32 v131, v0

	.amdhsa_kernel _Z10fwd_kernel6Params
		.amdhsa_group_segment_fixed_size 0
		.amdhsa_private_segment_fixed_size 0
		.amdhsa_kernarg_size 456
		.amdhsa_user_sgpr_count 2
		.amdhsa_user_sgpr_dispatch_ptr 0
		.amdhsa_user_sgpr_queue_ptr 0
		.amdhsa_user_sgpr_kernarg_segment_ptr 1
		.amdhsa_user_sgpr_dispatch_id 0
		.amdhsa_user_sgpr_kernarg_preload_length 0
		.amdhsa_user_sgpr_kernarg_preload_offset 0
		.amdhsa_user_sgpr_private_segment_size 0
		.amdhsa_uses_dynamic_stack 0
		.amdhsa_enable_private_segment 0
		.amdhsa_system_sgpr_workgroup_id_x 1
		.amdhsa_system_sgpr_workgroup_id_y 0
		.amdhsa_system_sgpr_workgroup_id_z 0
		.amdhsa_system_sgpr_workgroup_info 0
		.amdhsa_system_vgpr_workitem_id 2
		.amdhsa_next_free_vgpr 256
		.amdhsa_next_free_sgpr 102
		.amdhsa_accum_offset 256
		.amdhsa_reserve_vcc 1
		.amdhsa_float_round_mode_32 0
		.amdhsa_float_round_mode_16_64 0
		.amdhsa_float_denorm_mode_32 3
		.amdhsa_float_denorm_mode_16_64 3
		.amdhsa_dx10_clamp 1
		.amdhsa_ieee_mode 1
		.amdhsa_fp16_overflow 0
		.amdhsa_tg_split 0
		.amdhsa_exception_fp_ieee_invalid_op 0
		.amdhsa_exception_fp_denorm_src 0
		.amdhsa_exception_fp_ieee_div_zero 0
		.amdhsa_exception_fp_ieee_overflow 0
		.amdhsa_exception_fp_ieee_underflow 0
		.amdhsa_exception_fp_ieee_inexact 0
		.amdhsa_exception_int_div_zero 0
	.end_amdhsa_kernel

amdhsa.kernels:
  - .agpr_count:     0
    .args:
      - .offset:         0
        .size:           200
        .value_kind:     by_value
      - .offset:         200
        .size:           4
        .value_kind:     hidden_block_count_x
      - .offset:         204
        .size:           4
        .value_kind:     hidden_block_count_y
      - .offset:         208
        .size:           4
        .value_kind:     hidden_block_count_z
      - .offset:         212
        .size:           2
        .value_kind:     hidden_group_size_x
      - .offset:         214
        .size:           2
        .value_kind:     hidden_group_size_y
      - .offset:         216
        .size:           2
        .value_kind:     hidden_group_size_z
      - .offset:         218
        .size:           2
        .value_kind:     hidden_remainder_x
      - .offset:         220
        .size:           2
        .value_kind:     hidden_remainder_y
      - .offset:         222
        .size:           2
        .value_kind:     hidden_remainder_z
      - .offset:         240
        .size:           8
        .value_kind:     hidden_global_offset_x
      - .offset:         248
        .size:           8
        .value_kind:     hidden_global_offset_y
      - .offset:         256
        .size:           8
        .value_kind:     hidden_global_offset_z
      - .offset:         264
        .size:           2
        .value_kind:     hidden_grid_dims
      - .offset:         288
        .size:           8
        .value_kind:     hidden_multigrid_sync_arg
      - .offset:         320
        .size:           4
        .value_kind:     hidden_dynamic_lds_size
    .group_segment_fixed_size: 0
    .kernarg_segment_align: 8
    .kernarg_segment_size: 456
    .language:       OpenCL C
    .language_version:
      - 2
      - 0
    .max_flat_workgroup_size: 512
    .name:           _Z10fwd_kernel6Params
    .private_segment_fixed_size: 0
    .sgpr_count:     108
    .sgpr_spill_count: 20
    .symbol:         _Z10fwd_kernel6Params.kd
    .uniform_work_group_size: 1
    .uses_dynamic_stack: false
    .vgpr_count:     256
    .vgpr_spill_count: 0
    .wavefront_size: 64
